# v15 + grid barrier: all WGs spin on the global arrival counter (>= (k+1)*n_xcd) instead of the generation word bumped afterwards by the last leader
# baseline (speedup 1.0000x reference)
; __device__ __forceinline__ unsigned xb_ld(unsigned* p)              { return __hip_atomic_load(p, __ATOMIC_RELAXED, __HIP_MEMORY_SCOPE_AGENT); }
; __device__ __forceinline__ unsigned xb_add(unsigned* p, unsigned v) { return __hip_atomic_fetch_add(p, v, __ATOMIC_RELAXED, __HIP_MEMORY_SCOPE_AGENT); }
; #define XB_SPIN(cond, bar) do { unsigned _sp = 0; while (cond) { __builtin_amdgcn_s_sleep(1); \
;     if ((++_sp & 255u) == 0u) { if (xb_ld(&(bar)[XB_TMO])) break; if (_sp > XB_SPIN_CAP) { atomicAdd(&(bar)[XB_TMO], 1u); break; } } } } while (0)
; __device__ __forceinline__ void xcd_barrier(const XcdBarrier& b) {
;     ...
;         const unsigned old = xb_add(&bar[XB_XSUB(b.x)], 1u);
;         const unsigned gen = old / nloc;
;         if (old + 1u == (gen + 1u) * nloc) {
;             __builtin_amdgcn_fence(__ATOMIC_RELEASE, "agent");
;             asm volatile("s_waitcnt vmcnt(0)" ::: "memory");
;             const unsigned og = xb_add(&bar[XB_TOP], 1u);
;             const unsigned tg = og / nx;
;             if (og + 1u == (tg + 1u) * nx) xb_add(&bar[XB_TOPGEN], 1u);
;             else XB_SPIN(xb_ld(&bar[XB_TOPGEN]) == tg, bar);
;             __builtin_amdgcn_fence(__ATOMIC_ACQUIRE, "agent");
;             xb_add(&bar[XB_XGEN(b.x)], 1u);
;             asm volatile("s_waitcnt vmcnt(0)" ::: "memory");
;         } else {
;             XB_SPIN(xb_ld(&bar[XB_XGEN(b.x)]) == gen, bar);
.LBB0_1125:
	s_or_b64 exec, exec, s[2:3]
	v_cvt_f32_u32_e32 v4, v2
	s_waitcnt vmcnt(0)
	v_readfirstlane_b32 s2, v3
	v_sub_u32_e32 v3, 0, v2
	v_rcp_iflag_f32_e32 v4, v4
	v_add_u32_e32 v5, s2, v1
	v_mul_f32_e32 v4, 0x4f7ffffe, v4
	v_cvt_u32_f32_e32 v4, v4
	v_mul_lo_u32 v1, v3, v4
	v_mul_hi_u32 v1, v4, v1
	v_add_u32_e32 v1, v4, v1
	v_mul_hi_u32 v1, v5, v1
	v_mul_lo_u32 v3, v1, v2
	v_sub_u32_e32 v3, v5, v3
	v_add_u32_e32 v4, 1, v1
	v_cmp_ge_u32_e32 vcc, v3, v2
	s_nop 1
	v_cndmask_b32_e32 v1, v1, v4, vcc
	v_sub_u32_e32 v4, v3, v2
	v_cndmask_b32_e32 v3, v3, v4, vcc
	v_add_u32_e32 v4, 1, v1
	v_cmp_ge_u32_e32 vcc, v3, v2
	v_add_u32_e32 v3, 1, v5
	s_nop 0
	v_cndmask_b32_e32 v1, v1, v4, vcc
	v_mul_lo_u32 v4, v2, v1
	v_add_u32_e32 v2, v4, v2
	v_cmp_ne_u32_e32 vcc, v3, v2
	s_and_saveexec_b64 s[2:3], vcc
	s_xor_b64 s[2:3], exec, s[2:3]
	s_cbranch_execz .LBB0_1139
	v_readlane_b32 s4, v253, 33
	v_readlane_b32 s5, v253, 34
	s_waitcnt lgkmcnt(0)
	v_add_u32_e32 v17, 1, v1
	v_mul_lo_u32 v17, v17, v0
	s_nop 3
	global_load_dword v0, v185, s[4:5] sc1
	s_waitcnt vmcnt(0)
	v_cmp_lt_u32_e32 vcc, v0, v17
	s_and_saveexec_b64 s[6:7], vcc
	s_cbranch_execz .LBB0_1138
	s_mov_b32 s16, 1
	s_mov_b64 s[8:9], 0
	s_branch .LBB0_1129

; __device__ __forceinline__ unsigned xb_ld(unsigned* p)              { return __hip_atomic_load(p, __ATOMIC_RELAXED, __HIP_MEMORY_SCOPE_AGENT); }
; #define XB_SPIN(cond, bar) do { unsigned _sp = 0; while (cond) { __builtin_amdgcn_s_sleep(1); \
;     if ((++_sp & 255u) == 0u) { if (xb_ld(&(bar)[XB_TMO])) break; if (_sp > XB_SPIN_CAP) { atomicAdd(&(bar)[XB_TMO], 1u); break; } } } } while (0)
; __device__ __forceinline__ void xcd_barrier(const XcdBarrier& b) {
;     ...
;             XB_SPIN(xb_ld(&bar[XB_XGEN(b.x)]) == gen, bar);
.LBB0_1131:
	v_readlane_b32 s4, v253, 33
	v_readlane_b32 s5, v253, 34
	s_add_i32 s16, s16, 1
	s_mov_b64 s[14:15], -1
	s_nop 2
	global_load_dword v0, v185, s[4:5] sc1
	s_waitcnt vmcnt(0)
	v_cmp_ge_u32_e32 vcc, v0, v17
	s_orn2_b64 s[12:13], vcc, exec
	s_branch .LBB0_1128

; __device__ __forceinline__ unsigned xb_ld(unsigned* p)              { return __hip_atomic_load(p, __ATOMIC_RELAXED, __HIP_MEMORY_SCOPE_AGENT); }
; __device__ __forceinline__ unsigned xb_add(unsigned* p, unsigned v) { return __hip_atomic_fetch_add(p, v, __ATOMIC_RELAXED, __HIP_MEMORY_SCOPE_AGENT); }
; #define XB_SPIN(cond, bar) do { unsigned _sp = 0; while (cond) { __builtin_amdgcn_s_sleep(1); \
;     if ((++_sp & 255u) == 0u) { if (xb_ld(&(bar)[XB_TMO])) break; if (_sp > XB_SPIN_CAP) { atomicAdd(&(bar)[XB_TMO], 1u); break; } } } } while (0)
; __device__ __forceinline__ void xcd_barrier(const XcdBarrier& b) {
;     ...
;         if (old + 1u == (gen + 1u) * nloc) {
;             __builtin_amdgcn_fence(__ATOMIC_RELEASE, "agent");
;             asm volatile("s_waitcnt vmcnt(0)" ::: "memory");
;             const unsigned og = xb_add(&bar[XB_TOP], 1u);
;             const unsigned tg = og / nx;
;             if (og + 1u == (tg + 1u) * nx) xb_add(&bar[XB_TOPGEN], 1u);
;             else XB_SPIN(xb_ld(&bar[XB_TOPGEN]) == tg, bar);
.LBB0_1142:
	s_or_b64 exec, exec, s[4:5]
	s_waitcnt vmcnt(0)
	v_readfirstlane_b32 s2, v2
	v_cvt_f32_u32_e32 v2, v0
	v_sub_u32_e32 v3, 0, v0
	v_add_u32_e32 v1, s2, v1
	v_readlane_b32 s2, v253, 35
	v_rcp_iflag_f32_e32 v2, v2
	v_readlane_b32 s3, v253, 36
	s_mov_b64 s[6:7], -1
	v_mul_f32_e32 v2, 0x4f7ffffe, v2
	v_cvt_u32_f32_e32 v2, v2
	v_mul_lo_u32 v3, v3, v2
	v_mul_hi_u32 v3, v2, v3
	v_add_u32_e32 v2, v2, v3
	v_mul_hi_u32 v2, v1, v2
	v_mul_lo_u32 v3, v2, v0
	v_sub_u32_e32 v3, v1, v3
	v_cmp_ge_u32_e32 vcc, v3, v0
	v_add_u32_e32 v4, 1, v2
	v_add_u32_e32 v1, 1, v1
	v_cndmask_b32_e32 v2, v2, v4, vcc
	v_sub_u32_e32 v4, v3, v0
	v_cndmask_b32_e32 v3, v3, v4, vcc
	v_cmp_ge_u32_e32 vcc, v3, v0
	v_add_u32_e32 v3, 1, v2
	s_nop 0
	v_cndmask_b32_e32 v2, v2, v3, vcc
	v_mul_lo_u32 v3, v0, v2
	v_add_u32_e32 v0, v3, v0
	v_mov_b32_e32 v17, v0
	v_cmp_ne_u32_e32 vcc, v1, v0
	v_mov_b64_e32 v[0:1], s[2:3]
	s_and_saveexec_b64 s[2:3], vcc
	s_cbranch_execz .LBB0_1154
	v_readlane_b32 s4, v253, 33
	v_readlane_b32 s5, v253, 34
	s_nop 4
	global_load_dword v0, v185, s[4:5] sc1
	s_mov_b64 s[4:5], 0
	s_waitcnt vmcnt(0)
	v_cmp_lt_u32_e32 vcc, v0, v17
	s_and_saveexec_b64 s[6:7], vcc
	s_cbranch_execz .LBB0_1153
	s_mov_b32 s16, 1
	s_mov_b64 s[8:9], 0
	s_branch .LBB0_1146
